# P0: nt also on the HB / MEMN row stores
# speedup vs baseline: 1.0287x; 1.0039x over previous
.LBB0_163:
	v_mov_b32_e32 v68, v82
	v_mov_b32_e32 v69, v82
	v_pk_mul_f32 v[82:83], v[60:61], v[82:83]
	v_pk_mul_f32 v[68:69], v[62:63], v[68:69]
	s_waitcnt vmcnt(0)
	v_pk_mul_f32 v[64:65], v[82:83], v[64:65]
	v_pk_mul_f32 v[66:67], v[68:69], v[66:67]
	v_cvt_pk_bf16_f32 v64, v64, v65
	s_nop 0
	v_cvt_pk_bf16_f32 v65, v66, v67
	global_store_dwordx2 v[80:81], v[64:65], off offset:1536 nt

.LBB0_169:
	s_waitcnt lgkmcnt(0)
	v_add_f32_e32 v65, v65, v80
	v_fmamk_f32 v65, v65, 0x3a800000, v91
	v_rsq_f32_e32 v82, v65
	s_ashr_i32 s17, s16, 31
	s_lshl_b64 s[22:23], s[16:17], 11
	v_lshl_add_u64 v[80:81], v[76:77], 0, s[22:23]
	v_pk_mul_f32 v[92:93], v[0:1], v[82:83] op_sel_hi:[1,0]
	v_pk_mul_f32 v[84:85], v[2:3], v[82:83] op_sel_hi:[1,0]
	s_waitcnt vmcnt(0)
	v_pk_mul_f32 v[66:67], v[92:93], v[66:67]
	v_pk_mul_f32 v[68:69], v[84:85], v[68:69]
	v_cvt_pk_bf16_f32 v66, v66, v67
	s_and_b64 vcc, exec, s[4:5]
	v_cvt_pk_bf16_f32 v67, v68, v69
	global_store_dwordx2 v[80:81], v[66:67], off nt
	v_mov_b32_e32 v65, 1.0
	v_mov_b32_e32 v66, 1.0
	v_mov_b32_e32 v67, 1.0
	s_cbranch_vccnz .LBB0_171
	global_load_dwordx4 v[64:67], v[78:79], off offset:1024 nt
.LBB0_171:
	v_mov_b32_e32 v83, v82
	v_mov_b32_e32 v84, v82
	v_mov_b32_e32 v85, v82
	v_pk_mul_f32 v[92:93], v[4:5], v[82:83]
	v_pk_mul_f32 v[68:69], v[6:7], v[84:85]
	s_waitcnt vmcnt(0)
	v_pk_mul_f32 v[64:65], v[92:93], v[64:65]
	v_pk_mul_f32 v[66:67], v[68:69], v[66:67]
	v_cvt_pk_bf16_f32 v64, v64, v65
	s_and_b64 vcc, exec, s[4:5]
	v_cvt_pk_bf16_f32 v65, v66, v67
	global_store_dwordx2 v[80:81], v[64:65], off offset:512 nt
	v_mov_b32_e32 v64, 1.0
	v_mov_b32_e32 v66, 1.0
	v_mov_b32_e32 v67, 1.0
	v_mov_b32_e32 v68, 1.0
	v_mov_b32_e32 v69, 1.0
	s_cbranch_vccnz .LBB0_173
	global_load_dwordx4 v[66:69], v[78:79], off offset:2048 nt
.LBB0_173:
	v_pk_mul_f32 v[92:93], v[8:9], v[82:83]
	v_pk_mul_f32 v[84:85], v[10:11], v[84:85]
	s_waitcnt vmcnt(0)
	v_pk_mul_f32 v[66:67], v[92:93], v[66:67]
	v_pk_mul_f32 v[68:69], v[84:85], v[68:69]
	v_cvt_pk_bf16_f32 v66, v66, v67
	s_and_b64 vcc, exec, s[4:5]
	v_cvt_pk_bf16_f32 v67, v68, v69
	global_store_dwordx2 v[80:81], v[66:67], off offset:1024 nt
	v_mov_b32_e32 v65, 1.0
	v_mov_b32_e32 v66, 1.0
	v_mov_b32_e32 v67, 1.0
	s_cbranch_vccnz .LBB0_175
	global_load_dwordx4 v[64:67], v[78:79], off offset:3072 nt
.LBB0_175:
	v_pk_mul_f32 v[68:69], v[18:19], v[18:19]
	v_pk_mul_f32 v[84:85], v[16:17], v[16:17]
	s_and_b64 vcc, exec, s[4:5]
	v_pk_mov_b32 v[92:93], v[84:85], v[68:69] op_sel:[1,0]
	v_mov_b32_e32 v85, v69
	v_pk_add_f32 v[68:69], v[92:93], v[84:85]
	v_pk_mul_f32 v[84:85], v[22:23], v[22:23]
	v_pk_add_f32 v[68:69], v[68:69], v[68:69] op_sel_hi:[0,1]
	v_pk_mul_f32 v[92:93], v[20:21], v[20:21]
	v_mul_f32_e32 v68, v24, v24
	v_pk_mov_b32 v[94:95], v[92:93], v[84:85] op_sel:[1,0]
	v_mov_b32_e32 v93, v85
	v_pk_add_f32 v[84:85], v[94:95], v[92:93]
	v_pk_fma_f32 v[92:93], v[24:25], v[24:25], v[68:69] op_sel_hi:[1,1,0]
	v_mul_f32_e32 v68, v26, v26
	v_pk_add_f32 v[84:85], v[84:85], v[84:85] op_sel_hi:[0,1]
	v_pk_fma_f32 v[94:95], v[26:27], v[26:27], v[68:69] op_sel_hi:[1,1,0]
	v_mul_f32_e32 v92, v28, v28
	v_mul_f32_e32 v94, v29, v29
	v_mul_f32_e32 v68, v30, v30
	v_mul_f32_e32 v84, v31, v31
	v_pk_add_f32 v[92:93], v[92:93], v[94:95]
	v_pk_add_f32 v[68:69], v[68:69], v[84:85]
	s_nop 0
	v_pk_add_f32 v[68:69], v[92:93], v[68:69]
	s_nop 0
	v_add_f32_e32 v68, v68, v69
	ds_bpermute_b32 v69, v71, v68
	s_waitcnt lgkmcnt(0)
	v_add_f32_e32 v68, v68, v69
	ds_bpermute_b32 v69, v73, v68
	s_waitcnt lgkmcnt(0)
	v_add_f32_e32 v69, v68, v69
	ds_bpermute_b32 v84, v87, v69
	v_mov_b32_e32 v68, v82
	s_waitcnt lgkmcnt(0)
	v_add_f32_e32 v84, v69, v84
	ds_bpermute_b32 v85, v88, v84
	v_mov_b32_e32 v69, v82
	v_pk_mul_f32 v[68:69], v[14:15], v[68:69]
	v_pk_mul_f32 v[82:83], v[12:13], v[82:83]
	s_waitcnt vmcnt(0)
	v_pk_mul_f32 v[66:67], v[68:69], v[66:67]
	s_waitcnt lgkmcnt(0)
	v_add_f32_e32 v68, v84, v85
	ds_bpermute_b32 v69, v89, v68
	v_pk_mul_f32 v[64:65], v[82:83], v[64:65]
	s_nop 0
	v_cvt_pk_bf16_f32 v64, v64, v65
	v_cvt_pk_bf16_f32 v65, v66, v67
	global_store_dwordx2 v[80:81], v[64:65], off offset:1536 nt
	s_waitcnt lgkmcnt(0)
	v_add_f32_e32 v65, v68, v69
	ds_bpermute_b32 v80, v90, v65
	v_mov_b32_e32 v64, 1.0
	v_mov_b32_e32 v66, 1.0
	v_mov_b32_e32 v67, 1.0
	v_mov_b32_e32 v68, 1.0
	v_mov_b32_e32 v69, 1.0
	s_cbranch_vccnz .LBB0_177
	global_load_dwordx4 v[66:69], v[78:79], off nt
.LBB0_177:
	s_waitcnt lgkmcnt(0)
	v_add_f32_e32 v65, v65, v80
	v_fmamk_f32 v65, v65, 0x3a800000, v91
	v_rsq_f32_e32 v82, v65
	s_ashr_i32 s9, s8, 31
	s_lshl_b64 s[22:23], s[8:9], 11
	v_lshl_add_u64 v[80:81], v[76:77], 0, s[22:23]
	v_pk_mul_f32 v[92:93], v[16:17], v[82:83] op_sel_hi:[1,0]
	v_pk_mul_f32 v[84:85], v[18:19], v[82:83] op_sel_hi:[1,0]
	s_waitcnt vmcnt(0)
	v_pk_mul_f32 v[66:67], v[92:93], v[66:67]
	v_pk_mul_f32 v[68:69], v[84:85], v[68:69]
	v_cvt_pk_bf16_f32 v66, v66, v67
	s_and_b64 vcc, exec, s[4:5]
	v_cvt_pk_bf16_f32 v67, v68, v69
	global_store_dwordx2 v[80:81], v[66:67], off nt
	v_mov_b32_e32 v65, 1.0
	v_mov_b32_e32 v66, 1.0
	v_mov_b32_e32 v67, 1.0
	s_cbranch_vccnz .LBB0_179
	global_load_dwordx4 v[64:67], v[78:79], off offset:1024 nt
.LBB0_179:
	v_mov_b32_e32 v83, v82
	v_mov_b32_e32 v84, v82
	v_mov_b32_e32 v85, v82
	v_pk_mul_f32 v[92:93], v[20:21], v[82:83]
	v_pk_mul_f32 v[68:69], v[22:23], v[84:85]
	s_waitcnt vmcnt(0)
	v_pk_mul_f32 v[64:65], v[92:93], v[64:65]
	v_pk_mul_f32 v[66:67], v[68:69], v[66:67]
	v_cvt_pk_bf16_f32 v64, v64, v65
	s_and_b64 vcc, exec, s[4:5]
	v_cvt_pk_bf16_f32 v65, v66, v67
	global_store_dwordx2 v[80:81], v[64:65], off offset:512 nt
	v_mov_b32_e32 v64, 1.0
	v_mov_b32_e32 v66, 1.0
	v_mov_b32_e32 v67, 1.0
	v_mov_b32_e32 v68, 1.0
	v_mov_b32_e32 v69, 1.0
	s_cbranch_vccnz .LBB0_181
	global_load_dwordx4 v[66:69], v[78:79], off offset:2048 nt
.LBB0_181:
	v_pk_mul_f32 v[92:93], v[24:25], v[82:83]
	v_pk_mul_f32 v[84:85], v[26:27], v[84:85]
	s_waitcnt vmcnt(0)
	v_pk_mul_f32 v[66:67], v[92:93], v[66:67]
	v_pk_mul_f32 v[68:69], v[84:85], v[68:69]
	v_cvt_pk_bf16_f32 v66, v66, v67
	s_and_b64 vcc, exec, s[4:5]
	v_cvt_pk_bf16_f32 v67, v68, v69
	global_store_dwordx2 v[80:81], v[66:67], off offset:1024 nt
	v_mov_b32_e32 v65, 1.0
	v_mov_b32_e32 v66, 1.0
	v_mov_b32_e32 v67, 1.0
	s_cbranch_vccnz .LBB0_183
	global_load_dwordx4 v[64:67], v[78:79], off offset:3072 nt
.LBB0_183:
	s_add_i32 s22, s7, s15
	v_mov_b32_e32 v68, v82
	v_mov_b32_e32 v69, v82
	v_pk_mul_f32 v[82:83], v[28:29], v[82:83]
	s_cmpk_gt_i32 s22, 0x7ff
	v_pk_mul_f32 v[68:69], v[30:31], v[68:69]
	s_waitcnt vmcnt(0)
	v_pk_mul_f32 v[64:65], v[82:83], v[64:65]
	v_pk_mul_f32 v[66:67], v[68:69], v[66:67]
	v_cvt_pk_bf16_f32 v64, v64, v65
	s_nop 0
	v_cvt_pk_bf16_f32 v65, v66, v67
	global_store_dwordx2 v[80:81], v[64:65], off offset:1536 nt
	s_cbranch_scc0 .LBB0_185
	s_andn2_b64 vcc, exec, s[20:21]
	s_cbranch_vccnz .LBB0_164
	s_branch .LBB0_186

.LBB0_188:
	s_waitcnt lgkmcnt(0)
	v_add_f32_e32 v65, v65, v80
	v_fmamk_f32 v65, v65, 0x3a800000, v91
	v_rsq_f32_e32 v82, v65
	s_ashr_i32 s15, s14, 31
	s_lshl_b64 s[20:21], s[14:15], 11
	v_lshl_add_u64 v[80:81], v[76:77], 0, s[20:21]
	v_pk_mul_f32 v[92:93], v[32:33], v[82:83] op_sel_hi:[1,0]
	v_pk_mul_f32 v[84:85], v[34:35], v[82:83] op_sel_hi:[1,0]
	s_waitcnt vmcnt(0)
	v_pk_mul_f32 v[66:67], v[92:93], v[66:67]
	v_pk_mul_f32 v[68:69], v[84:85], v[68:69]
	v_cvt_pk_bf16_f32 v66, v66, v67
	s_and_b64 vcc, exec, s[4:5]
	v_cvt_pk_bf16_f32 v67, v68, v69
	global_store_dwordx2 v[80:81], v[66:67], off nt
	v_mov_b32_e32 v65, 1.0
	v_mov_b32_e32 v66, 1.0
	v_mov_b32_e32 v67, 1.0
	s_cbranch_vccnz .LBB0_190
	global_load_dwordx4 v[64:67], v[78:79], off offset:1024 nt
.LBB0_190:
	v_mov_b32_e32 v83, v82
	v_mov_b32_e32 v84, v82
	v_mov_b32_e32 v85, v82
	v_pk_mul_f32 v[92:93], v[36:37], v[82:83]
	v_pk_mul_f32 v[68:69], v[38:39], v[84:85]
	s_waitcnt vmcnt(0)
	v_pk_mul_f32 v[64:65], v[92:93], v[64:65]
	v_pk_mul_f32 v[66:67], v[68:69], v[66:67]
	v_cvt_pk_bf16_f32 v64, v64, v65
	s_and_b64 vcc, exec, s[4:5]
	v_cvt_pk_bf16_f32 v65, v66, v67
	global_store_dwordx2 v[80:81], v[64:65], off offset:512 nt
	v_mov_b32_e32 v64, 1.0
	v_mov_b32_e32 v66, 1.0
	v_mov_b32_e32 v67, 1.0
	v_mov_b32_e32 v68, 1.0
	v_mov_b32_e32 v69, 1.0
	s_cbranch_vccnz .LBB0_192
	global_load_dwordx4 v[66:69], v[78:79], off offset:2048 nt
.LBB0_192:
	v_pk_mul_f32 v[92:93], v[40:41], v[82:83]
	v_pk_mul_f32 v[84:85], v[42:43], v[84:85]
	s_waitcnt vmcnt(0)
	v_pk_mul_f32 v[66:67], v[92:93], v[66:67]
	v_pk_mul_f32 v[68:69], v[84:85], v[68:69]
	v_cvt_pk_bf16_f32 v66, v66, v67
	s_and_b64 vcc, exec, s[4:5]
	v_cvt_pk_bf16_f32 v67, v68, v69
	global_store_dwordx2 v[80:81], v[66:67], off offset:1024 nt
	v_mov_b32_e32 v65, 1.0
	v_mov_b32_e32 v66, 1.0
	v_mov_b32_e32 v67, 1.0
	s_cbranch_vccnz .LBB0_194
	global_load_dwordx4 v[64:67], v[78:79], off offset:3072 nt
.LBB0_194:
	v_pk_mul_f32 v[68:69], v[50:51], v[50:51]
	v_pk_mul_f32 v[84:85], v[48:49], v[48:49]
	s_and_b64 vcc, exec, s[4:5]
	v_pk_mov_b32 v[92:93], v[84:85], v[68:69] op_sel:[1,0]
	v_mov_b32_e32 v85, v69
	v_pk_add_f32 v[68:69], v[92:93], v[84:85]
	v_pk_mul_f32 v[84:85], v[54:55], v[54:55]
	v_pk_add_f32 v[68:69], v[68:69], v[68:69] op_sel_hi:[0,1]
	v_pk_mul_f32 v[92:93], v[52:53], v[52:53]
	v_mul_f32_e32 v68, v56, v56
	v_pk_mov_b32 v[94:95], v[92:93], v[84:85] op_sel:[1,0]
	v_mov_b32_e32 v93, v85
	v_pk_add_f32 v[84:85], v[94:95], v[92:93]
	v_pk_fma_f32 v[92:93], v[56:57], v[56:57], v[68:69] op_sel_hi:[1,1,0]
	v_mul_f32_e32 v68, v58, v58
	v_pk_add_f32 v[84:85], v[84:85], v[84:85] op_sel_hi:[0,1]
	v_pk_fma_f32 v[94:95], v[58:59], v[58:59], v[68:69] op_sel_hi:[1,1,0]
	v_mul_f32_e32 v92, v60, v60
	v_mul_f32_e32 v94, v61, v61
	v_mul_f32_e32 v84, v62, v62
	v_mul_f32_e32 v68, v63, v63
	v_pk_add_f32 v[92:93], v[92:93], v[94:95]
	v_pk_add_f32 v[68:69], v[84:85], v[68:69]
	s_nop 0
	v_pk_add_f32 v[68:69], v[92:93], v[68:69]
	s_nop 0
	v_add_f32_e32 v68, v68, v69
	ds_bpermute_b32 v69, v71, v68
	s_waitcnt lgkmcnt(0)
	v_add_f32_e32 v68, v68, v69
	ds_bpermute_b32 v69, v73, v68
	s_waitcnt lgkmcnt(0)
	v_add_f32_e32 v69, v68, v69
	ds_bpermute_b32 v84, v87, v69
	v_mov_b32_e32 v68, v82
	s_waitcnt lgkmcnt(0)
	v_add_f32_e32 v84, v69, v84
	ds_bpermute_b32 v85, v88, v84
	v_mov_b32_e32 v69, v82
	v_pk_mul_f32 v[68:69], v[46:47], v[68:69]
	v_pk_mul_f32 v[82:83], v[44:45], v[82:83]
	s_waitcnt vmcnt(0)
	v_pk_mul_f32 v[66:67], v[68:69], v[66:67]
	s_waitcnt lgkmcnt(0)
	v_add_f32_e32 v68, v84, v85
	ds_bpermute_b32 v69, v89, v68
	v_pk_mul_f32 v[64:65], v[82:83], v[64:65]
	s_nop 0
	v_cvt_pk_bf16_f32 v64, v64, v65
	v_cvt_pk_bf16_f32 v65, v66, v67
	global_store_dwordx2 v[80:81], v[64:65], off offset:1536 nt
	s_waitcnt lgkmcnt(0)
	v_add_f32_e32 v65, v68, v69
	ds_bpermute_b32 v80, v90, v65
	v_mov_b32_e32 v64, 1.0
	v_mov_b32_e32 v66, 1.0
	v_mov_b32_e32 v67, 1.0
	v_mov_b32_e32 v68, 1.0
	v_mov_b32_e32 v69, 1.0
	s_cbranch_vccnz .LBB0_196
	global_load_dwordx4 v[66:69], v[78:79], off nt
.LBB0_196:
	s_waitcnt lgkmcnt(0)
	v_add_f32_e32 v65, v65, v80
	v_fmamk_f32 v65, v65, 0x3a800000, v91
	v_rsq_f32_e32 v82, v65
	s_ashr_i32 s13, s12, 31
	s_lshl_b64 s[20:21], s[12:13], 11
	v_lshl_add_u64 v[80:81], v[76:77], 0, s[20:21]
	v_pk_mul_f32 v[92:93], v[48:49], v[82:83] op_sel_hi:[1,0]
	v_pk_mul_f32 v[84:85], v[50:51], v[82:83] op_sel_hi:[1,0]
	s_waitcnt vmcnt(0)
	v_pk_mul_f32 v[66:67], v[92:93], v[66:67]
	v_pk_mul_f32 v[68:69], v[84:85], v[68:69]
	v_cvt_pk_bf16_f32 v66, v66, v67
	s_and_b64 vcc, exec, s[4:5]
	v_cvt_pk_bf16_f32 v67, v68, v69
	global_store_dwordx2 v[80:81], v[66:67], off nt
	v_mov_b32_e32 v65, 1.0
	v_mov_b32_e32 v66, 1.0
	v_mov_b32_e32 v67, 1.0
	s_cbranch_vccnz .LBB0_198
	global_load_dwordx4 v[64:67], v[78:79], off offset:1024 nt
.LBB0_198:
	v_mov_b32_e32 v83, v82
	v_mov_b32_e32 v84, v82
	v_mov_b32_e32 v85, v82
	v_pk_mul_f32 v[92:93], v[52:53], v[82:83]
	v_pk_mul_f32 v[68:69], v[54:55], v[84:85]
	s_waitcnt vmcnt(0)
	v_pk_mul_f32 v[64:65], v[92:93], v[64:65]
	v_pk_mul_f32 v[66:67], v[68:69], v[66:67]
	v_cvt_pk_bf16_f32 v64, v64, v65
	s_and_b64 vcc, exec, s[4:5]
	v_cvt_pk_bf16_f32 v65, v66, v67
	global_store_dwordx2 v[80:81], v[64:65], off offset:512 nt
	v_mov_b32_e32 v64, 1.0
	v_mov_b32_e32 v66, 1.0
	v_mov_b32_e32 v67, 1.0
	v_mov_b32_e32 v68, 1.0
	v_mov_b32_e32 v69, 1.0
	s_cbranch_vccnz .LBB0_200
	global_load_dwordx4 v[66:69], v[78:79], off offset:2048 nt
.LBB0_200:
	v_pk_mul_f32 v[92:93], v[56:57], v[82:83]
	v_pk_mul_f32 v[84:85], v[58:59], v[84:85]
	s_waitcnt vmcnt(0)
	v_pk_mul_f32 v[66:67], v[92:93], v[66:67]
	v_pk_mul_f32 v[68:69], v[84:85], v[68:69]
	v_cvt_pk_bf16_f32 v66, v66, v67
	s_and_b64 vcc, exec, s[4:5]
	v_cvt_pk_bf16_f32 v67, v68, v69
	global_store_dwordx2 v[80:81], v[66:67], off offset:1024 nt
	v_mov_b32_e32 v65, 1.0
	v_mov_b32_e32 v66, 1.0
	v_mov_b32_e32 v67, 1.0
	s_cbranch_vccnz .LBB0_163
	global_load_dwordx4 v[64:67], v[78:79], off offset:3072 nt
	s_branch .LBB0_163

.LBB0_208:
	s_waitcnt vmcnt(7)
	v_mul_f32_e32 v70, v1, v1
	s_waitcnt lgkmcnt(0)
	v_mul_f32_e32 v71, v3, v3
	v_fmac_f32_e32 v70, v0, v0
	v_fmac_f32_e32 v71, v2, v2
	v_add_f32_e32 v70, v70, v71
	s_waitcnt vmcnt(6)
	v_mul_f32_e32 v71, v5, v5
	v_mul_f32_e32 v72, v7, v7
	v_fmac_f32_e32 v71, v4, v4
	v_fmac_f32_e32 v72, v6, v6
	v_add_f32_e32 v71, v71, v72
	v_add_f32_e32 v70, v70, v71
	s_waitcnt vmcnt(5)
	v_mul_f32_e32 v71, v9, v9
	v_mul_f32_e32 v72, v11, v11
	v_fmac_f32_e32 v71, v8, v8
	v_fmac_f32_e32 v72, v10, v10
	v_add_f32_e32 v71, v71, v72
	v_add_f32_e32 v70, v71, v70
	s_waitcnt vmcnt(4)
	v_mul_f32_e32 v71, v13, v13
	v_mul_f32_e32 v72, v15, v15
	v_fmac_f32_e32 v71, v12, v12
	v_fmac_f32_e32 v72, v14, v14
	v_add_f32_e32 v71, v71, v72
	v_add_f32_e32 v71, v71, v70
	v_and_b32_e32 v70, 64, v68
	v_add_u32_e32 v78, 64, v70
	v_xor_b32_e32 v70, 1, v68
	v_cmp_lt_i32_e32 vcc, v70, v78
	s_ashr_i32 s15, s14, 31
	s_lshl_b64 s[20:21], s[14:15], 11
	v_cndmask_b32_e32 v70, v68, v70, vcc
	v_lshlrev_b32_e32 v70, 2, v70
	ds_bpermute_b32 v72, v70, v71
	v_lshl_add_u64 v[80:81], v[66:67], 0, s[20:21]
	v_cvt_pk_bf16_f32 v76, v0, v1
	v_cvt_pk_bf16_f32 v77, v2, v3
	global_store_dwordx2 v[80:81], v[76:77], off nt
	s_waitcnt lgkmcnt(0)
	v_add_f32_e32 v72, v71, v72
	v_xor_b32_e32 v71, 2, v68
	v_cmp_lt_i32_e32 vcc, v71, v78
	v_cvt_pk_bf16_f32 v76, v4, v5
	v_cvt_pk_bf16_f32 v77, v6, v7
	global_store_dwordx2 v[80:81], v[76:77], off offset:512 nt
	v_xor_b32_e32 v76, 32, v68
	v_cndmask_b32_e32 v71, v68, v71, vcc
	v_lshlrev_b32_e32 v71, 2, v71
	ds_bpermute_b32 v74, v71, v72
	v_cvt_pk_bf16_f32 v82, v8, v9
	v_cvt_pk_bf16_f32 v83, v10, v11
	global_store_dwordx2 v[80:81], v[82:83], off offset:1024 nt
	v_cvt_pk_bf16_f32 v82, v12, v13
	s_waitcnt lgkmcnt(0)
	v_add_f32_e32 v74, v72, v74
	v_xor_b32_e32 v72, 4, v68
	v_cmp_lt_i32_e32 vcc, v72, v78
	v_cvt_pk_bf16_f32 v83, v14, v15
	global_store_dwordx2 v[80:81], v[82:83], off offset:1536 nt
	s_nop 0
	v_cndmask_b32_e32 v72, v68, v72, vcc
	v_lshlrev_b32_e32 v72, 2, v72
	ds_bpermute_b32 v75, v72, v74
	s_waitcnt lgkmcnt(0)
	v_add_f32_e32 v75, v74, v75
	v_xor_b32_e32 v74, 8, v68
	v_cmp_lt_i32_e32 vcc, v74, v78
	s_nop 1
	v_cndmask_b32_e32 v74, v68, v74, vcc
	v_lshlrev_b32_e32 v74, 2, v74
	ds_bpermute_b32 v79, v74, v75
	s_waitcnt lgkmcnt(0)
	v_add_f32_e32 v79, v75, v79
	v_xor_b32_e32 v75, 16, v68
	v_cmp_lt_i32_e32 vcc, v75, v78
	s_nop 1
	v_cndmask_b32_e32 v75, v68, v75, vcc
	v_lshlrev_b32_e32 v75, 2, v75
	ds_bpermute_b32 v84, v75, v79
	v_cmp_lt_i32_e32 vcc, v76, v78
	s_waitcnt lgkmcnt(0)
	v_add_f32_e32 v77, v79, v84
	v_cndmask_b32_e32 v76, v68, v76, vcc
	v_lshlrev_b32_e32 v76, 2, v76
	ds_bpermute_b32 v78, v76, v77
	s_and_saveexec_b64 s[20:21], s[4:5]
	s_cbranch_execz .LBB0_210
	s_waitcnt lgkmcnt(0)
	v_add_f32_e32 v77, v77, v78
	v_fmamk_f32 v77, v77, 0x3a800000, v69
	v_rsq_f32_e32 v77, v77
	s_lshl_b64 s[28:29], s[14:15], 2
	s_add_u32 s28, s22, s28
	s_addc_u32 s29, s23, s29
	global_store_dword v73, v77, s[28:29]
.LBB0_210:
	s_or_b64 exec, exec, s[20:21]
	s_waitcnt vmcnt(7)
	v_mul_f32_e32 v77, v17, v17
	s_waitcnt lgkmcnt(0)
	v_mul_f32_e32 v78, v19, v19
	v_fmac_f32_e32 v77, v16, v16
	v_fmac_f32_e32 v78, v18, v18
	v_add_f32_e32 v77, v77, v78
	s_waitcnt vmcnt(6)
	v_mul_f32_e32 v78, v21, v21
	v_mul_f32_e32 v79, v23, v23
	v_fmac_f32_e32 v78, v20, v20
	v_fmac_f32_e32 v79, v22, v22
	v_add_f32_e32 v78, v78, v79
	v_add_f32_e32 v77, v77, v78
	s_waitcnt vmcnt(5)
	v_mul_f32_e32 v78, v25, v25
	v_mul_f32_e32 v79, v27, v27
	v_fmac_f32_e32 v78, v24, v24
	v_fmac_f32_e32 v79, v26, v26
	v_add_f32_e32 v78, v78, v79
	v_add_f32_e32 v77, v78, v77
	s_waitcnt vmcnt(4)
	v_mul_f32_e32 v78, v29, v29
	v_mul_f32_e32 v79, v31, v31
	v_fmac_f32_e32 v78, v28, v28
	v_fmac_f32_e32 v79, v30, v30
	v_add_f32_e32 v78, v78, v79
	v_add_f32_e32 v77, v78, v77
	ds_bpermute_b32 v78, v70, v77
	s_ashr_i32 s9, s8, 31
	s_lshl_b64 s[20:21], s[8:9], 11
	v_lshl_add_u64 v[80:81], v[66:67], 0, s[20:21]
	s_waitcnt lgkmcnt(0)
	v_add_f32_e32 v77, v77, v78
	ds_bpermute_b32 v78, v71, v77
	s_waitcnt lgkmcnt(0)
	v_add_f32_e32 v77, v77, v78
	ds_bpermute_b32 v78, v72, v77
	s_waitcnt lgkmcnt(0)
	v_add_f32_e32 v77, v77, v78
	ds_bpermute_b32 v82, v74, v77
	v_cvt_pk_bf16_f32 v78, v16, v17
	v_cvt_pk_bf16_f32 v79, v18, v19
	global_store_dwordx2 v[80:81], v[78:79], off nt
	v_cvt_pk_bf16_f32 v78, v20, v21
	s_waitcnt lgkmcnt(0)
	v_add_f32_e32 v77, v77, v82
	ds_bpermute_b32 v84, v75, v77
	v_cvt_pk_bf16_f32 v79, v22, v23
	global_store_dwordx2 v[80:81], v[78:79], off offset:512 nt
	v_cvt_pk_bf16_f32 v82, v24, v25
	v_cvt_pk_bf16_f32 v83, v26, v27
	s_waitcnt lgkmcnt(0)
	v_add_f32_e32 v77, v77, v84
	ds_bpermute_b32 v78, v76, v77
	global_store_dwordx2 v[80:81], v[82:83], off offset:1024 nt
	v_cvt_pk_bf16_f32 v82, v28, v29
	v_cvt_pk_bf16_f32 v83, v30, v31
	global_store_dwordx2 v[80:81], v[82:83], off offset:1536 nt
	s_and_saveexec_b64 s[20:21], s[4:5]
	s_cbranch_execnz .LBB0_213
	s_or_b64 exec, exec, s[20:21]
	s_add_i32 s20, s24, s6
	s_cmpk_gt_i32 s20, 0x7fff
	s_cbranch_scc0 .LBB0_214

.LBB0_215:
	v_mul_f32_e32 v77, v33, v33
	s_waitcnt lgkmcnt(0)
	v_mul_f32_e32 v78, v35, v35
	v_fmac_f32_e32 v77, v32, v32
	v_fmac_f32_e32 v78, v34, v34
	v_add_f32_e32 v77, v77, v78
	v_mul_f32_e32 v78, v37, v37
	v_mul_f32_e32 v79, v39, v39
	v_fmac_f32_e32 v78, v36, v36
	v_fmac_f32_e32 v79, v38, v38
	v_add_f32_e32 v78, v78, v79
	v_add_f32_e32 v77, v78, v77
	v_mul_f32_e32 v78, v41, v41
	v_mul_f32_e32 v79, v43, v43
	v_fmac_f32_e32 v78, v40, v40
	v_fmac_f32_e32 v79, v42, v42
	v_add_f32_e32 v78, v78, v79
	v_add_f32_e32 v77, v78, v77
	v_mul_f32_e32 v78, v45, v45
	v_mul_f32_e32 v79, v47, v47
	v_fmac_f32_e32 v78, v44, v44
	v_fmac_f32_e32 v79, v46, v46
	v_add_f32_e32 v78, v78, v79
	v_add_f32_e32 v77, v78, v77
	ds_bpermute_b32 v78, v70, v77
	s_ashr_i32 s13, s12, 31
	s_lshl_b64 s[6:7], s[12:13], 11
	v_lshl_add_u64 v[80:81], v[66:67], 0, s[6:7]
	s_waitcnt lgkmcnt(0)
	v_add_f32_e32 v77, v77, v78
	ds_bpermute_b32 v78, v71, v77
	s_waitcnt lgkmcnt(0)
	v_add_f32_e32 v77, v77, v78
	ds_bpermute_b32 v78, v72, v77
	s_waitcnt lgkmcnt(0)
	v_add_f32_e32 v77, v77, v78
	ds_bpermute_b32 v82, v74, v77
	v_cvt_pk_bf16_f32 v78, v32, v33
	v_cvt_pk_bf16_f32 v79, v34, v35
	global_store_dwordx2 v[80:81], v[78:79], off nt
	v_cvt_pk_bf16_f32 v78, v36, v37
	s_waitcnt lgkmcnt(0)
	v_add_f32_e32 v77, v77, v82
	ds_bpermute_b32 v84, v75, v77
	v_cvt_pk_bf16_f32 v79, v38, v39
	global_store_dwordx2 v[80:81], v[78:79], off offset:512 nt
	v_cvt_pk_bf16_f32 v82, v40, v41
	v_cvt_pk_bf16_f32 v83, v42, v43
	s_waitcnt lgkmcnt(0)
	v_add_f32_e32 v77, v77, v84
	ds_bpermute_b32 v78, v76, v77
	global_store_dwordx2 v[80:81], v[82:83], off offset:1024 nt
	v_cvt_pk_bf16_f32 v82, v44, v45
	v_cvt_pk_bf16_f32 v83, v46, v47
	global_store_dwordx2 v[80:81], v[82:83], off offset:1536 nt
	s_and_saveexec_b64 s[6:7], s[4:5]
	s_cbranch_execz .LBB0_217
	s_waitcnt lgkmcnt(0)
	v_add_f32_e32 v77, v77, v78
	v_fmamk_f32 v77, v77, 0x3a800000, v69
	v_rsq_f32_e32 v77, v77
	s_lshl_b64 s[18:19], s[12:13], 2
	s_add_u32 s18, s22, s18
	s_addc_u32 s19, s23, s19
	global_store_dword v73, v77, s[18:19]
.LBB0_217:
	s_or_b64 exec, exec, s[6:7]
	v_mul_f32_e32 v77, v49, v49
	s_waitcnt lgkmcnt(0)
	v_mul_f32_e32 v78, v51, v51
	v_fmac_f32_e32 v77, v48, v48
	v_fmac_f32_e32 v78, v50, v50
	v_add_f32_e32 v77, v77, v78
	v_mul_f32_e32 v78, v53, v53
	v_mul_f32_e32 v79, v55, v55
	v_fmac_f32_e32 v78, v52, v52
	v_fmac_f32_e32 v79, v54, v54
	v_add_f32_e32 v78, v78, v79
	v_add_f32_e32 v77, v78, v77
	v_mul_f32_e32 v78, v57, v57
	v_mul_f32_e32 v79, v59, v59
	v_fmac_f32_e32 v78, v56, v56
	v_fmac_f32_e32 v79, v58, v58
	v_add_f32_e32 v78, v78, v79
	v_add_f32_e32 v77, v78, v77
	v_mul_f32_e32 v78, v61, v61
	v_mul_f32_e32 v79, v63, v63
	v_fmac_f32_e32 v78, v60, v60
	v_fmac_f32_e32 v79, v62, v62
	v_add_f32_e32 v78, v78, v79
	v_add_f32_e32 v77, v78, v77
	ds_bpermute_b32 v70, v70, v77
	s_ashr_i32 s11, s10, 31
	s_lshl_b64 s[6:7], s[10:11], 11
	v_lshl_add_u64 v[78:79], v[66:67], 0, s[6:7]
	s_waitcnt lgkmcnt(0)
	v_add_f32_e32 v70, v77, v70
	ds_bpermute_b32 v71, v71, v70
	s_waitcnt lgkmcnt(0)
	v_add_f32_e32 v70, v70, v71
	ds_bpermute_b32 v71, v72, v70
	s_waitcnt lgkmcnt(0)
	v_add_f32_e32 v72, v70, v71
	ds_bpermute_b32 v74, v74, v72
	v_cvt_pk_bf16_f32 v70, v48, v49
	v_cvt_pk_bf16_f32 v71, v50, v51
	global_store_dwordx2 v[78:79], v[70:71], off nt
	v_cvt_pk_bf16_f32 v70, v52, v53
	s_waitcnt lgkmcnt(0)
	v_add_f32_e32 v72, v72, v74
	ds_bpermute_b32 v77, v75, v72
	v_cvt_pk_bf16_f32 v71, v54, v55
	global_store_dwordx2 v[78:79], v[70:71], off offset:512 nt
	v_cvt_pk_bf16_f32 v74, v56, v57
	v_cvt_pk_bf16_f32 v75, v58, v59
	s_waitcnt lgkmcnt(0)
	v_add_f32_e32 v70, v72, v77
	ds_bpermute_b32 v71, v76, v70
	global_store_dwordx2 v[78:79], v[74:75], off offset:1024 nt
	v_cvt_pk_bf16_f32 v74, v60, v61
	v_cvt_pk_bf16_f32 v75, v62, v63
	global_store_dwordx2 v[78:79], v[74:75], off offset:1536 nt
	s_and_saveexec_b64 s[6:7], s[4:5]
	s_cbranch_execz .LBB0_204
	s_waitcnt lgkmcnt(0)
	v_add_f32_e32 v70, v70, v71
	v_fmamk_f32 v70, v70, 0x3a800000, v69
	v_rsq_f32_e32 v70, v70
	s_lshl_b64 s[18:19], s[10:11], 2
	s_add_u32 s18, s22, s18
	s_addc_u32 s19, s23, s19
	global_store_dword v73, v70, s[18:19]
	s_branch .LBB0_204
